# D and F sample-row tails: epilogue loads (gates, row sums) issued before the split-K fragment loads so their round trip overlaps the GEMM
# baseline (speedup 1.0000x reference)
; __device__ __forceinline__ f32x4 unpack4(u32x2 w) { return (f32x4){bflo(w.x), bfhi(w.x), bflo(w.y), bfhi(w.y)}; }
; __device__ __forceinline__ int lane_fresh() { int l; asm volatile("v_mbcnt_lo_u32_b32 %0, -1, 0\n\tv_mbcnt_hi_u32_b32 %0, -1, %0" : "=v"(l)); return l; }
; #define MFMA16(a, b, c) __builtin_amdgcn_mfma_f32_16x16x32_bf16((a), (b), (c), 0, 0, 0)
; template <int NT, class FA, class FB, class FL>
; __device__ __forceinline__ void skgemm(FA aptr, FB bptr, FL ldf, const int KS, const int wv) {
;   float* part = (float*)g_shm;
;   const int lane = lane_fresh(), fr = lane & 15, fq = lane >> 4;
;   __syncthreads();
; #pragma unroll
;   for (int i = 0; i < NT; ++i) {
;     f32x4 acc = {0.f, 0.f, 0.f, 0.f};
;     const int ld = ldf(i);
;     const u16* ap = aptr(i) + (size_t)fr * ld + wv * KS + fq * 8;
;     const u16* bp = bptr(i) + (size_t)fr * ld + wv * KS + fq * 8;
; #pragma unroll 8
;     for (int k = 0; k < KS; k += 32) acc = MFMA16(*(const bf16x8*)(bp + k), *(const bf16x8*)(ap + k), acc);
;     *(f32x4*)(part + ((i * 8 + wv) * 64 + lane) * 4) = acc;
;   }
;   __syncthreads();
; __device__ __forceinline__ void phaseD(const Params& p, const int wv, const int rep) {
;     ...
;   for (int gb = blockIdx.x; gb < 256; gb += gridDim.x) {
;     const int task0 = gb * 2, mt = task0 >> 6, nt0 = task0 & 63, r0 = TP + mt * 16;
;     skgemm<8>([&](int i) { const int br = i & 3; return br == 0 ? GM + (size_t)r0 * 512 : br == 1 ? Y + (size_t)r0 * 1024 : br == 2 ? Y + (size_t)r0 * 1024 + 512 : XA + (size_t)r0 * 512; },
;               [&](int i) { const int br = i & 3, c0 = (nt0 + (i >> 2)) * 16; return br == 0 ? WGM + (size_t)c0 * 512 : br == 1 ? WSSD + (size_t)c0 * 1024 : br == 2 ? WSSD + (size_t)c0 * 1024 + 512 : WXA + (size_t)c0 * 512; },
;               [&](int i) { const int br = i & 3; return (br == 1 || br == 2) ? 1024 : 512; }, 64, wv);
;     if (wv < 2) {
;       const int lane_e = lane_fresh(), fr = lane_e & 15, fq = lane_e >> 4;
;       const int row = r0 + fr, col = (nt0 + wv) * 16 + fq * 4;
;       const u16* gp_ = GATE + (size_t)row * 3072 + col;
;       f32x4 g0 = unpack4(*(const u32x2*)gp_), g1 = unpack4(*(const u32x2*)(gp_ + 1024)), g2 = unpack4(*(const u32x2*)(gp_ + 2048));
.LBB0_918:
	s_ashr_i32 s0, s19, 1
	s_and_b32 s0, s0, -16
	s_addk_i32 s0, 0x4000
	s_ashr_i32 s1, s0, 31
	s_and_b32 s20, s11, 62
	s_lshl_b64 s[22:23], s[0:1], 10
	v_mbcnt_lo_u32_b32 v3, -1, 0
	v_mbcnt_hi_u32_b32 v3, -1, v3
	s_add_u32 s24, s66, s22
	v_and_b32_e32 v20, 15, v3
	v_ashrrev_i32_e32 v0, 1, v3
	v_and_b32_e32 v4, -8, v0
	s_addc_u32 s25, s67, s23
	v_lshlrev_b32_e32 v0, 10, v20
	s_lshl_b32 s12, s20, 4
	s_lshl_b32 s13, s20, 14
	v_lshl_add_u64 v[6:7], s[24:25], 0, v[0:1]
	s_add_u32 s24, s70, s13
	v_ashrrev_i32_e32 v5, 31, v4
	s_addc_u32 s25, s71, 0
	v_lshlrev_b64 v[68:69], 1, v[4:5]
	v_lshl_add_u64 v[4:5], s[24:25], 0, v[0:1]
	v_lshl_add_u64 v[6:7], v[6:7], 0, s[8:9]
	v_lshl_add_u64 v[4:5], v[4:5], 0, s[8:9]
	v_lshl_add_u64 v[16:17], v[6:7], 0, v[68:69]
	v_lshl_add_u64 v[8:9], v[4:5], 0, v[68:69]
	s_cmp_gt_u32 s90, 1
	s_cbranch_scc1 .Ldh_skip
	v_mbcnt_lo_u32_b32 v238, -1, 0
	v_mbcnt_hi_u32_b32 v238, -1, v238
	v_mov_b64_e32 v[244:245], s[26:27]
	v_and_or_b32 v240, v238, 15, s0
	v_ashrrev_i32_e32 v238, 2, v238
	s_or_b32 s100, s20, s90
	v_and_b32_e32 v238, -4, v238
	v_lshl_add_u32 v242, s100, 4, v238
	v_mad_i64_i32 v[246:247], vcc, v240, s16, v[244:245]
	v_ashrrev_i32_e32 v241, 31, v240
	v_readlane_b32 s100, v251, 4
	v_lshlrev_b64 v[244:245], 7, v[240:241]
	v_readlane_b32 s101, v251, 5
	v_ashrrev_i32_e32 v243, 31, v242
	v_lshlrev_b64 v[242:243], 1, v[242:243]
	s_nop 1
	v_lshl_add_u64 v[248:249], s[100:101], 0, v[244:245]
	global_load_dwordx4 v[200:203], v[248:249], off
	global_load_dwordx4 v[204:207], v[248:249], off offset:16
	global_load_dwordx4 v[208:211], v[248:249], off offset:64
	global_load_dwordx4 v[212:215], v[248:249], off offset:80
	global_load_dwordx4 v[216:219], v[248:249], off offset:32
	global_load_dwordx4 v[220:223], v[248:249], off offset:96
	v_lshl_add_u64 v[244:245], v[246:247], 0, v[242:243]
	global_load_dwordx2 v[224:225], v[244:245], off
	global_load_dwordx2 v[226:227], v[244:245], off offset:2048
	global_load_dwordx4 v[228:231], v[248:249], off offset:48
	global_load_dwordx4 v[232:235], v[248:249], off offset:112
	v_add_co_u32_e32 v244, vcc, s17, v244
	s_nop 1
	v_addc_co_u32_e32 v245, vcc, 0, v245, vcc
	global_load_dwordx2 v[236:237], v[244:245], off
.Ldh_skip:
	s_barrier
	global_load_dwordx4 v[4:7], v[8:9], off
	s_nop 0
	global_load_dwordx4 v[8:11], v[8:9], off offset:64
	s_nop 0
	global_load_dwordx4 v[12:15], v[16:17], off
	s_nop 0
	global_load_dwordx4 v[16:19], v[16:17], off offset:64
	s_lshl_b64 s[24:25], s[0:1], 11
	s_add_u32 s24, s48, s24
	s_addc_u32 s25, s49, s25
	v_lshlrev_b32_e32 v64, 11, v20
	v_mov_b32_e32 v65, v1
	s_lshl_b32 s1, s20, 15
	v_lshl_add_u64 v[24:25], s[24:25], 0, v[64:65]
	s_add_u32 s24, s72, s1
	s_addc_u32 s25, s73, 0
	s_add_u32 s22, s68, s22
	s_addc_u32 s23, s69, s23
	v_lshl_add_u64 v[52:53], s[22:23], 0, v[0:1]
	s_add_u32 s22, s74, s13
	v_lshl_add_u64 v[20:21], s[24:25], 0, v[64:65]
	s_addc_u32 s23, s75, 0
	s_or_b32 s1, s12, 16
	v_lshl_add_u64 v[20:21], v[20:21], 0, s[8:9]
	v_lshl_add_u64 v[52:53], v[52:53], 0, s[8:9]
	s_lshl_b32 s12, s1, 10
	v_lshl_add_u64 v[48:49], v[20:21], 0, v[68:69]
	v_lshl_add_u64 v[24:25], v[24:25], 0, s[8:9]
	v_lshl_add_u64 v[60:61], v[52:53], 0, v[68:69]
	v_lshl_add_u64 v[52:53], s[22:23], 0, v[0:1]
	s_add_u32 s22, s70, s12
	global_load_dwordx4 v[20:23], v[48:49], off
	v_lshl_add_u64 v[40:41], v[24:25], 0, v[68:69]
	v_lshl_add_u64 v[52:53], v[52:53], 0, s[8:9]
	s_addc_u32 s23, s71, 0
	global_load_dwordx4 v[24:27], v[40:41], off
	global_load_dwordx4 v[28:31], v[48:49], off offset:1024
	global_load_dwordx4 v[32:35], v[40:41], off offset:1024
	v_lshl_add_u64 v[66:67], v[52:53], 0, v[68:69]
	v_lshl_add_u64 v[52:53], s[22:23], 0, v[0:1]
	v_lshl_add_u64 v[52:53], v[52:53], 0, s[8:9]
	v_lshl_add_u64 v[70:71], v[52:53], 0, v[68:69]
	global_load_dwordx4 v[36:39], v[40:41], off offset:64
	s_nop 0
	global_load_dwordx4 v[40:43], v[40:41], off offset:1088
	s_nop 0
	global_load_dwordx4 v[44:47], v[48:49], off offset:64
	s_nop 0
	global_load_dwordx4 v[48:51], v[48:49], off offset:1088
	s_lshl_b32 s1, s1, 11
	s_add_u32 s22, s72, s1
	s_addc_u32 s23, s73, 0
	s_waitcnt vmcnt(9)
	v_mfma_f32_16x16x32_bf16 v[4:7], v[4:7], v[12:15], 0
	global_load_dwordx4 v[52:55], v[70:71], off
	s_waitcnt vmcnt(9)
	v_mfma_f32_16x16x32_bf16 v[4:7], v[8:11], v[16:19], v[4:7]
	global_load_dwordx4 v[8:11], v[66:67], off
	global_load_dwordx4 v[56:59], v[60:61], off
	s_nop 0
	global_load_dwordx4 v[60:63], v[60:61], off offset:64
	s_waitcnt vmcnt(8)
	v_mfma_f32_16x16x32_bf16 v[28:31], v[28:31], v[32:35], 0
	v_mfma_f32_16x16x32_bf16 v[20:23], v[20:23], v[24:27], 0
	s_waitcnt vmcnt(4)
	v_mfma_f32_16x16x32_bf16 v[28:31], v[48:51], v[40:43], v[28:31]
	v_lshl_add_u64 v[48:49], s[22:23], 0, v[64:65]
	v_lshl_add_u64 v[48:49], v[48:49], 0, s[8:9]
	v_lshl_add_u64 v[72:73], v[48:49], 0, v[68:69]
	v_mfma_f32_16x16x32_bf16 v[20:23], v[44:47], v[36:39], v[20:23]
	global_load_dwordx4 v[44:47], v[66:67], off offset:64
	global_load_dwordx4 v[48:51], v[72:73], off
	s_nop 0
	global_load_dwordx4 v[64:67], v[70:71], off offset:64
	s_add_u32 s22, s74, s12
	s_addc_u32 s23, s75, 0
	v_lshl_add_u64 v[70:71], s[22:23], 0, v[0:1]
	v_lshl_add_u64 v[70:71], v[70:71], 0, s[8:9]
	v_lshl_add_u64 v[68:69], v[70:71], 0, v[68:69]
	v_add_u32_e32 v0, s88, v3
	v_lshl_add_u32 v0, v0, 4, 16
	s_and_b64 vcc, exec, s[4:5]
	s_waitcnt vmcnt(6)
	v_mfma_f32_16x16x32_bf16 v[12:15], v[52:55], v[12:15], 0
	global_load_dwordx4 v[52:55], v[72:73], off offset:1024
	s_waitcnt vmcnt(5)
	v_mfma_f32_16x16x32_bf16 v[8:11], v[8:11], v[56:59], 0
	s_waitcnt vmcnt(3)
	v_mfma_f32_16x16x32_bf16 v[8:11], v[44:47], v[60:63], v[8:11]
	global_load_dwordx4 v[44:47], v[72:73], off offset:64
	s_waitcnt vmcnt(3)
	v_mfma_f32_16x16x32_bf16 v[24:27], v[48:51], v[24:27], 0
	global_load_dwordx4 v[48:51], v[72:73], off offset:1088
	s_waitcnt vmcnt(3)
	v_mfma_f32_16x16x32_bf16 v[12:15], v[64:67], v[16:19], v[12:15]
	global_load_dwordx4 v[16:19], v[68:69], off offset:64
	s_waitcnt vmcnt(3)
	v_mfma_f32_16x16x32_bf16 v[32:35], v[52:55], v[32:35], 0
	global_load_dwordx4 v[52:55], v[68:69], off
	ds_write_b128 v0, v[4:7]
	ds_write_b128 v0, v[20:23] offset:8192
	ds_write_b128 v0, v[28:31] offset:16384
	ds_write_b128 v0, v[8:11] offset:24576
	ds_write_b128 v0, v[12:15] offset:32768
	s_waitcnt vmcnt(3)
	v_mfma_f32_16x16x32_bf16 v[24:27], v[44:47], v[36:39], v[24:27]
	s_waitcnt vmcnt(2)
	v_mfma_f32_16x16x32_bf16 v[4:7], v[48:51], v[40:43], v[32:35]
	s_waitcnt vmcnt(0)
	v_mfma_f32_16x16x32_bf16 v[52:55], v[52:55], v[56:59], 0
	v_mfma_f32_16x16x32_bf16 v[8:11], v[16:19], v[60:63], v[52:55]
	s_nop 2
	ds_write_b128 v0, v[24:27] offset:40960
	s_nop 0
	ds_write_b128 v0, v[4:7] offset:49152
	s_nop 1
	ds_write_b128 v0, v[8:11] offset:57344
	s_waitcnt lgkmcnt(0)
	s_barrier
; __device__ __forceinline__ f32x4 unpack4(u32x2 w) { return (f32x4){bflo(w.x), bfhi(w.x), bflo(w.y), bfhi(w.y)}; }
; __device__ __forceinline__ int lane_fresh() { int l; asm volatile("v_mbcnt_lo_u32_b32 %0, -1, 0\n\tv_mbcnt_hi_u32_b32 %0, -1, %0" : "=v"(l)); return l; }
; __device__ __forceinline__ void phaseD(const Params& p, const int wv, const int rep) {
;     ...
;     if (wv < 2) {
;       const int lane_e = lane_fresh(), fr = lane_e & 15, fq = lane_e >> 4;
;       const int row = r0 + fr, col = (nt0 + wv) * 16 + fq * 4;
;       const u16* gp_ = GATE + (size_t)row * 3072 + col;
;       f32x4 g0 = unpack4(*(const u32x2*)gp_), g1 = unpack4(*(const u32x2*)(gp_ + 1024)), g2 = unpack4(*(const u32x2*)(gp_ + 2048));
;       float rs[2];
; #pragma unroll
;       for (int gg = 0; gg < 2; ++gg) {
;         const float* ps = YPS + (size_t)row * 32 + gg * 16;
;         f32x4 a = *(const f32x4*)ps + *(const f32x4*)(ps + 4) + *(const f32x4*)(ps + 8) + *(const f32x4*)(ps + 12);
;         rs[gg] = rsqrtf((a[0] + a[1] + a[2] + a[3]) * (1.f / 512.f) + EPS);
;       }
;       f32x4 a0 = skreduce(wv * 4 + 0), a1 = skreduce(wv * 4 + 1), a2 = skreduce(wv * 4 + 2), a3 = skreduce(wv * 4 + 3);
;       f32x4 o = g0 * a0 + g1 * (a1 * rs[0] + a2 * rs[1]) + g2 * a3;
	s_cbranch_vccnz .LBB0_917
	v_mbcnt_lo_u32_b32 v0, -1, 0
	v_mbcnt_hi_u32_b32 v0, -1, v0
	v_mov_b64_e32 v[8:9], s[26:27]
	v_and_or_b32 v4, v0, 15, s0
	v_ashrrev_i32_e32 v0, 2, v0
	s_or_b32 s0, s20, s90
	v_and_b32_e32 v0, -4, v0
	v_lshl_add_u32 v6, s0, 4, v0
	v_mad_i64_i32 v[32:33], s[0:1], v4, s16, v[8:9]
	v_ashrrev_i32_e32 v5, 31, v4
	v_readlane_b32 s0, v251, 4
	v_lshlrev_b64 v[8:9], 7, v[4:5]
	v_readlane_b32 s1, v251, 5
	v_ashrrev_i32_e32 v7, 31, v6
	v_lshlrev_b64 v[6:7], 1, v[6:7]
	v_lshl_add_u64 v[36:37], s[0:1], 0, v[8:9]
	v_mov_b32_e32 v8, v200
	v_mov_b32_e32 v9, v201
	v_mov_b32_e32 v10, v202
	v_mov_b32_e32 v11, v203
	v_mov_b32_e32 v12, v204
	v_mov_b32_e32 v13, v205
	v_mov_b32_e32 v14, v206
	v_mov_b32_e32 v15, v207
	v_mov_b32_e32 v16, v208
	v_mov_b32_e32 v17, v209
	v_mov_b32_e32 v18, v210
	v_mov_b32_e32 v19, v211
	v_mov_b32_e32 v20, v212
	v_mov_b32_e32 v21, v213
	v_mov_b32_e32 v22, v214
	v_mov_b32_e32 v23, v215
	v_mov_b32_e32 v24, v216
	v_mov_b32_e32 v25, v217
	v_mov_b32_e32 v26, v218
	v_mov_b32_e32 v27, v219
	v_mov_b32_e32 v28, v220
	v_mov_b32_e32 v29, v221
	v_mov_b32_e32 v30, v222
	v_mov_b32_e32 v31, v223
	v_lshl_add_u64 v[40:41], v[32:33], 0, v[6:7]
	v_mov_b32_e32 v72, v224
	v_mov_b32_e32 v73, v225
	v_mov_b32_e32 v74, v226
	v_mov_b32_e32 v75, v227
	v_mov_b32_e32 v32, v228
	v_mov_b32_e32 v33, v229
	v_mov_b32_e32 v34, v230
	v_mov_b32_e32 v35, v231
	s_nop 0
	v_mov_b32_e32 v36, v232
	v_mov_b32_e32 v37, v233
	v_mov_b32_e32 v38, v234
	v_mov_b32_e32 v39, v235
	v_add_co_u32_e32 v40, vcc, s17, v40
	v_lshlrev_b64 v[4:5], 11, v[4:5]
	s_nop 0
	v_addc_co_u32_e32 v41, vcc, 0, v41, vcc
	v_mov_b32_e32 v76, v236
	v_mov_b32_e32 v77, v237
	v_mbcnt_lo_u32_b32 v0, -1, 0
	v_mbcnt_hi_u32_b32 v0, -1, v0
	v_lshl_add_u64 v[4:5], s[2:3], 0, v[4:5]
	v_lshl_add_u32 v0, v0, 4, s10
	ds_read_b128 v[40:43], v0
	ds_read_b128 v[44:47], v0 offset:1024
	ds_read_b128 v[48:51], v0 offset:2048
	ds_read_b128 v[52:55], v0 offset:3072
	ds_read_b128 v[56:59], v0 offset:4096
	ds_read_b128 v[60:63], v0 offset:5120
	ds_read_b128 v[64:67], v0 offset:6144
	ds_read_b128 v[68:71], v0 offset:7168
	v_mbcnt_lo_u32_b32 v0, -1, 0
	v_mbcnt_hi_u32_b32 v0, -1, v0
	s_waitcnt lgkmcnt(7)
	v_pk_add_f32 v[40:41], v[40:41], 0 op_sel_hi:[1,0]
	v_lshl_add_u32 v3, v0, 4, s10
	s_waitcnt lgkmcnt(6)
	v_pk_add_f32 v[40:41], v[40:41], v[44:45]
	v_pk_add_f32 v[42:43], v[42:43], 0 op_sel_hi:[1,0]
	s_waitcnt lgkmcnt(5)
	v_pk_add_f32 v[40:41], v[40:41], v[48:49]
	v_pk_add_f32 v[42:43], v[42:43], v[46:47]
	s_waitcnt lgkmcnt(4)
	v_pk_add_f32 v[40:41], v[40:41], v[52:53]
	v_pk_add_f32 v[42:43], v[42:43], v[50:51]
	s_waitcnt lgkmcnt(3)
	v_pk_add_f32 v[40:41], v[40:41], v[56:57]
	v_pk_add_f32 v[42:43], v[42:43], v[54:55]
	s_waitcnt lgkmcnt(2)
	v_pk_add_f32 v[40:41], v[40:41], v[60:61]
	v_pk_add_f32 v[42:43], v[42:43], v[58:59]
	v_lshl_add_u64 v[4:5], v[4:5], 0, v[6:7]
	v_pk_add_f32 v[42:43], v[42:43], v[62:63]
	s_waitcnt vmcnt(9)
	v_pk_add_f32 v[10:11], v[10:11], v[14:15]
	v_pk_add_f32 v[8:9], v[8:9], v[12:13]
	s_waitcnt vmcnt(7)
	v_pk_add_f32 v[14:15], v[16:17], v[20:21]
	v_pk_add_f32 v[12:13], v[18:19], v[22:23]
	s_waitcnt vmcnt(6)
	v_pk_add_f32 v[8:9], v[8:9], v[24:25]
	s_waitcnt vmcnt(5)
	v_pk_add_f32 v[14:15], v[14:15], v[28:29]
	v_pk_add_f32 v[10:11], v[10:11], v[26:27]
	v_pk_add_f32 v[12:13], v[12:13], v[30:31]
	s_waitcnt vmcnt(2)
	v_pk_add_f32 v[8:9], v[8:9], v[32:33]
	s_waitcnt vmcnt(1)
	v_pk_add_f32 v[14:15], v[14:15], v[36:37]
	v_pk_add_f32 v[10:11], v[10:11], v[34:35]
	v_pk_add_f32 v[12:13], v[12:13], v[38:39]
	v_mov_b32_e32 v16, v14
	v_mov_b32_e32 v17, v8
	v_mov_b32_e32 v8, v15
	v_mov_b32_e32 v14, v12
	v_mov_b32_e32 v15, v10
	v_pk_add_f32 v[8:9], v[16:17], v[8:9]
	v_mov_b32_e32 v10, v13
	v_pk_add_f32 v[8:9], v[14:15], v[8:9]
	ds_read_b128 v[12:15], v3 offset:9216
	v_pk_add_f32 v[8:9], v[10:11], v[8:9]
	s_waitcnt lgkmcnt(2)
	v_pk_add_f32 v[16:17], v[40:41], v[64:65]
	v_pk_fma_f32 v[8:9], v[8:9], s[14:15], v[2:3] op_sel_hi:[1,0,0]
	s_waitcnt lgkmcnt(1)
	v_pk_add_f32 v[36:37], v[16:17], v[68:69]
	v_mul_f32_e32 v0, 0x4b800000, v9
	v_mul_f32_e32 v10, 0x4b800000, v8
	v_cmp_gt_f32_e32 vcc, s18, v9
	v_cmp_gt_f32_e64 s[0:1], s18, v8
	ds_read_b128 v[16:19], v3 offset:10240
	v_cndmask_b32_e32 v0, v9, v0, vcc
	v_cndmask_b32_e64 v8, v8, v10, s[0:1]
	v_rsq_f32_e32 v0, v0
	v_rsq_f32_e32 v8, v8
	v_pk_add_f32 v[42:43], v[42:43], v[66:67]
	v_lshlrev_b32_e32 v24, 16, v74
	v_mul_f32_e32 v9, 0x45800000, v0
	v_mul_f32_e32 v10, 0x45800000, v8
	v_cndmask_b32_e32 v0, v0, v9, vcc
	v_cndmask_b32_e64 v32, v8, v10, s[0:1]
	ds_read_b128 v[8:11], v3 offset:8192
	v_pk_add_f32 v[34:35], v[42:43], v[70:71]
	v_and_b32_e32 v25, 0xffff0000, v74
	v_lshlrev_b32_e32 v26, 16, v75
	v_and_b32_e32 v27, 0xffff0000, v75
	s_waitcnt lgkmcnt(0)
; __device__ __forceinline__ u32x2 pack4(f32x4 v) { u32x2 r; r.x = cvt_pk(v[0], v[1]); r.y = cvt_pk(v[2], v[3]); return r; }
; __device__ __forceinline__ void phaseD(const Params& p, const int wv, const int rep) {
;     ...
;       f32x4 a0 = skreduce(wv * 4 + 0), a1 = skreduce(wv * 4 + 1), a2 = skreduce(wv * 4 + 2), a3 = skreduce(wv * 4 + 3);
;       f32x4 o = g0 * a0 + g1 * (a1 * rs[0] + a2 * rs[1]) + g2 * a3;
;       *(u32x2*)(MERGED + (size_t)row * 1024 + col) = pack4(o);
	v_pk_add_f32 v[10:11], v[10:11], 0 op_sel_hi:[1,0]
	v_pk_add_f32 v[38:39], v[8:9], 0 op_sel_hi:[1,0]
	v_pk_add_f32 v[14:15], v[10:11], v[14:15]
	ds_read_b128 v[8:11], v3 offset:11264
	v_pk_add_f32 v[38:39], v[38:39], v[12:13]
	v_pk_add_f32 v[18:19], v[14:15], v[18:19]
	ds_read_b128 v[12:15], v3 offset:12288
	v_pk_add_f32 v[38:39], v[38:39], v[16:17]
	s_waitcnt lgkmcnt(1)
	v_pk_add_f32 v[10:11], v[18:19], v[10:11]
	ds_read_b128 v[16:19], v3 offset:13312
	v_pk_add_f32 v[38:39], v[38:39], v[8:9]
	s_waitcnt lgkmcnt(1)
	v_pk_add_f32 v[14:15], v[10:11], v[14:15]
	ds_read_b128 v[8:11], v3 offset:14336
	v_pk_add_f32 v[12:13], v[38:39], v[12:13]
	s_waitcnt lgkmcnt(1)
	v_pk_add_f32 v[18:19], v[14:15], v[18:19]
	v_pk_add_f32 v[38:39], v[12:13], v[16:17]
	ds_read_b128 v[12:15], v3 offset:15360
	v_mbcnt_lo_u32_b32 v3, -1, 0
	v_mbcnt_hi_u32_b32 v3, -1, v3
	s_waitcnt lgkmcnt(1)
	v_pk_add_f32 v[10:11], v[18:19], v[10:11]
	v_lshl_add_u32 v3, v3, 4, s10
	ds_read_b128 v[16:19], v3 offset:16384
	v_pk_add_f32 v[38:39], v[38:39], v[8:9]
	s_waitcnt lgkmcnt(1)
	v_pk_add_f32 v[40:41], v[10:11], v[14:15]
	ds_read_b128 v[8:11], v3 offset:17408
	v_pk_add_f32 v[38:39], v[38:39], v[12:13]
	s_waitcnt lgkmcnt(1)
	v_pk_add_f32 v[18:19], v[18:19], 0 op_sel_hi:[1,0]
	ds_read_b128 v[12:15], v3 offset:18432
	v_pk_add_f32 v[42:43], v[16:17], 0 op_sel_hi:[1,0]
	s_waitcnt lgkmcnt(1)
	v_pk_add_f32 v[10:11], v[18:19], v[10:11]
	ds_read_b128 v[16:19], v3 offset:19456
	v_pk_add_f32 v[42:43], v[42:43], v[8:9]
	s_waitcnt lgkmcnt(1)
	v_pk_add_f32 v[14:15], v[10:11], v[14:15]
	ds_read_b128 v[8:11], v3 offset:20480
	v_pk_add_f32 v[42:43], v[42:43], v[12:13]
	s_waitcnt lgkmcnt(1)
	v_pk_add_f32 v[18:19], v[14:15], v[18:19]
	ds_read_b128 v[12:15], v3 offset:21504
	v_pk_add_f32 v[42:43], v[42:43], v[16:17]
	s_waitcnt lgkmcnt(1)
	v_pk_add_f32 v[10:11], v[18:19], v[10:11]
	ds_read_b128 v[16:19], v3 offset:22528
	v_pk_add_f32 v[8:9], v[42:43], v[8:9]
	s_waitcnt lgkmcnt(1)
	v_pk_add_f32 v[14:15], v[10:11], v[14:15]
	v_pk_add_f32 v[42:43], v[8:9], v[12:13]
	ds_read_b128 v[8:11], v3 offset:23552
	v_mbcnt_lo_u32_b32 v3, -1, 0
	v_mbcnt_hi_u32_b32 v3, -1, v3
	s_waitcnt lgkmcnt(1)
	v_pk_add_f32 v[18:19], v[14:15], v[18:19]
	v_lshl_add_u32 v3, v3, 4, s10
	ds_read_b128 v[12:15], v3 offset:24576
	v_pk_add_f32 v[42:43], v[42:43], v[16:17]
	s_waitcnt lgkmcnt(1)
	v_pk_add_f32 v[44:45], v[18:19], v[10:11]
	ds_read_b128 v[16:19], v3 offset:25600
	v_pk_add_f32 v[42:43], v[42:43], v[8:9]
	ds_read_b128 v[8:11], v3 offset:26624
	s_waitcnt lgkmcnt(2)
	v_pk_add_f32 v[14:15], v[14:15], 0 op_sel_hi:[1,0]
	v_pk_add_f32 v[46:47], v[12:13], 0 op_sel_hi:[1,0]
	s_waitcnt lgkmcnt(1)
	v_pk_add_f32 v[18:19], v[14:15], v[18:19]
	ds_read_b128 v[12:15], v3 offset:27648
	v_pk_add_f32 v[46:47], v[46:47], v[16:17]
	s_waitcnt lgkmcnt(1)
	v_pk_add_f32 v[10:11], v[18:19], v[10:11]
	ds_read_b128 v[16:19], v3 offset:28672
	v_pk_add_f32 v[8:9], v[46:47], v[8:9]
	s_waitcnt lgkmcnt(1)
	v_pk_add_f32 v[14:15], v[10:11], v[14:15]
	v_pk_add_f32 v[46:47], v[8:9], v[12:13]
	ds_read_b128 v[8:11], v3 offset:29696
	s_waitcnt lgkmcnt(1)
	v_pk_add_f32 v[48:49], v[14:15], v[18:19]
	ds_read_b128 v[12:15], v3 offset:30720
	v_pk_add_f32 v[46:47], v[46:47], v[16:17]
	ds_read_b128 v[16:19], v3 offset:31744
	s_waitcnt lgkmcnt(2)
	v_pk_add_f32 v[10:11], v[48:49], v[10:11]
	v_pk_add_f32 v[8:9], v[46:47], v[8:9]
	s_waitcnt lgkmcnt(1)
	v_pk_add_f32 v[10:11], v[10:11], v[14:15]
	v_pk_add_f32 v[8:9], v[8:9], v[12:13]
	v_pk_mul_f32 v[12:13], v[32:33], v[44:45] op_sel_hi:[0,1]
	v_pk_mul_f32 v[14:15], v[32:33], v[42:43] op_sel_hi:[0,1]
	v_pk_fma_f32 v[14:15], v[0:1], v[38:39], v[14:15] op_sel_hi:[0,1,1]
	v_pk_fma_f32 v[12:13], v[0:1], v[40:41], v[12:13] op_sel_hi:[0,1,1]
	v_lshlrev_b32_e32 v20, 16, v72
	v_and_b32_e32 v21, 0xffff0000, v72
	v_lshlrev_b32_e32 v22, 16, v73
	v_and_b32_e32 v23, 0xffff0000, v73
	v_pk_mul_f32 v[12:13], v[12:13], v[26:27]
	v_pk_mul_f32 v[14:15], v[14:15], v[24:25]
	s_waitcnt vmcnt(0)
	v_lshlrev_b32_e32 v28, 16, v76
	v_and_b32_e32 v29, 0xffff0000, v76
	v_lshlrev_b32_e32 v30, 16, v77
	v_and_b32_e32 v31, 0xffff0000, v77
	s_waitcnt lgkmcnt(0)
	v_pk_add_f32 v[10:11], v[10:11], v[18:19]
	v_pk_add_f32 v[8:9], v[8:9], v[16:17]
	v_pk_fma_f32 v[14:15], v[36:37], v[20:21], v[14:15]
	v_pk_fma_f32 v[12:13], v[34:35], v[22:23], v[12:13]
	v_pk_fma_f32 v[8:9], v[8:9], v[28:29], v[14:15]
	v_pk_fma_f32 v[10:11], v[10:11], v[30:31], v[12:13]
	v_cvt_pk_bf16_f32 v8, v8, v9
	v_cvt_pk_bf16_f32 v9, v10, v11
	global_store_dwordx2 v[4:5], v[8:9], off
	s_branch .LBB0_917

; __device__ __forceinline__ int lane_fresh() { int l; asm volatile("v_mbcnt_lo_u32_b32 %0, -1, 0\n\tv_mbcnt_hi_u32_b32 %0, -1, %0" : "=v"(l)); return l; }
; #define MFMA16(a, b, c) __builtin_amdgcn_mfma_f32_16x16x32_bf16((a), (b), (c), 0, 0, 0)
; template <int NT, class FA, class FB, class FL>
; __device__ __forceinline__ void skgemm(FA aptr, FB bptr, FL ldf, const int KS, const int wv) {
;   float* part = (float*)g_shm;
;   const int lane = lane_fresh(), fr = lane & 15, fq = lane >> 4;
;   __syncthreads();
; #pragma unroll
;   for (int i = 0; i < NT; ++i) {
;     f32x4 acc = {0.f, 0.f, 0.f, 0.f};
;     const int ld = ldf(i);
;     const u16* ap = aptr(i) + (size_t)fr * ld + wv * KS + fq * 8;
;     const u16* bp = bptr(i) + (size_t)fr * ld + wv * KS + fq * 8;
; #pragma unroll 8
;     for (int k = 0; k < KS; k += 32) acc = MFMA16(*(const bf16x8*)(bp + k), *(const bf16x8*)(ap + k), acc);
;     *(f32x4*)(part + ((i * 8 + wv) * 64 + lane) * 4) = acc;
;   }
;   __syncthreads();
; __device__ __forceinline__ void phaseF(const Params& p, const int wv, const int rep) {
;     ...
;   for (int gb = blockIdx.x; gb < 256; gb += gridDim.x) {
;     const int task0 = gb * 8, mt = task0 >> 8, nt0 = task0 & 255;
;     const u16* Ab = H2B + (size_t)(TP + mt * 16) * 1024;
;     skgemm<8>([&](int) { return Ab; }, [&](int i) { return WUP + (size_t)((nt0 + i) * 16) * 1024; }, [&](int) { return 1024; }, 128, wv);
;     {
;       const int lane_e = lane_fresh(), fr = lane_e & 15, fq = lane_e >> 4;
;       const int ntl = nt0 + wv, row = TP + mt * 16 + fr, col = ntl * 16 + fq * 4;
;       const float* ps = PSS + (size_t)(row - TP) * 64 + fq * 16;
;       f32x4 a4 = *(const f32x4*)ps + *(const f32x4*)(ps + 4) + *(const f32x4*)(ps + 8) + *(const f32x4*)(ps + 12);
;       float sq = a4[0] + a4[1] + a4[2] + a4[3];
.LBB0_1077:
	s_and_b32 s98, s43, 63
	s_lshl_b32 s98, s98, 2
	s_lshr_b32 s99, s43, 6
	s_lshl_b32 s99, s99, 5
	s_addk_i32 s99, 0x4000
	v_mbcnt_lo_u32_b32 v3, -1, 0
	v_mbcnt_hi_u32_b32 v3, -1, v3
	s_lshl_b32 s28, s99, 11
	s_add_u32 s52, s8, s28
	s_addc_u32 s53, s9, 0
	s_lshl_b32 s28, s98, 15
	s_add_u32 s28, s33, s28
	s_addc_u32 s29, s44, 0
	v_and_b32_e32 v200, 15, v3
	v_lshlrev_b32_e32 v200, 11, v200
	v_lshrrev_b32_e32 v201, 4, v3
	v_lshl_add_u32 v200, v201, 4, v200
	v_add_u32_e32 v200, s4, v200
	v_lshl_add_u32 v201, v3, 4, s30
	s_lshr_b32 s100, s90, 2
	s_lshl_b32 s100, s100, 4
	s_add_i32 s100, s100, s99
	v_and_or_b32 v220, v3, 15, s100
	v_ashrrev_i32_e32 v221, 31, v220
	v_and_b32_e32 v222, -16, v3
	v_lshlrev_b64 v[224:225], 8, v[220:221]
	v_ashrrev_i32_e32 v223, 31, v222
	v_lshl_add_u64 v[224:225], s[10:11], 0, v[224:225]
	v_lshl_add_u64 v[222:223], v[222:223], 2, v[224:225]
	v_lshl_add_u64 v[226:227], v[222:223], 0, s[26:27]
	v_add_co_u32_e32 v222, vcc, s41, v222
	s_nop 1
	v_addc_co_u32_e32 v223, vcc, -1, v223, vcc
	global_load_dwordx4 v[204:207], v[222:223], off
	global_load_dwordx4 v[208:211], v[226:227], off offset:16
	global_load_dwordx4 v[212:215], v[226:227], off offset:32
	global_load_dwordx4 v[216:219], v[226:227], off offset:48
	s_barrier
	global_load_dwordx4 v[64:67], v200, s[52:53]
	global_load_dwordx4 v[68:71], v200, s[52:53] offset:64
	global_load_dwordx4 v[72:75], v200, s[52:53] offset:128
	global_load_dwordx4 v[76:79], v200, s[52:53] offset:192
	global_load_dwordx4 v[96:99], v200, s[28:29]
	global_load_dwordx4 v[100:103], v200, s[28:29] offset:64
	global_load_dwordx4 v[104:107], v200, s[28:29] offset:128
	global_load_dwordx4 v[108:111], v200, s[28:29] offset:192
	s_add_u32 s28, s28, 0x8000
	s_addc_u32 s29, s29, 0
	global_load_dwordx4 v[112:115], v200, s[28:29]
	global_load_dwordx4 v[116:119], v200, s[28:29] offset:64
	global_load_dwordx4 v[120:123], v200, s[28:29] offset:128
	global_load_dwordx4 v[124:127], v200, s[28:29] offset:192
	s_add_u32 s28, s28, 0x8000
	s_addc_u32 s29, s29, 0
	global_load_dwordx4 v[128:131], v200, s[28:29]
	global_load_dwordx4 v[132:135], v200, s[28:29] offset:64
	global_load_dwordx4 v[136:139], v200, s[28:29] offset:128
	global_load_dwordx4 v[140:143], v200, s[28:29] offset:192
	s_add_u32 s28, s28, 0x8000
	s_addc_u32 s29, s29, 0
	global_load_dwordx4 v[144:147], v200, s[28:29]
	global_load_dwordx4 v[148:151], v200, s[28:29] offset:64
	global_load_dwordx4 v[152:155], v200, s[28:29] offset:128
	global_load_dwordx4 v[156:159], v200, s[28:29] offset:192
	s_add_u32 s28, s28, 0x8000
	s_addc_u32 s29, s29, 0
	s_add_u32 s52, s52, 0x8000
	s_addc_u32 s53, s53, 0
	global_load_dwordx4 v[80:83], v200, s[52:53]
	global_load_dwordx4 v[84:87], v200, s[52:53] offset:64
	global_load_dwordx4 v[88:91], v200, s[52:53] offset:128
	global_load_dwordx4 v[92:95], v200, s[52:53] offset:192
	s_add_i32 s43, s43, s54
	s_add_i32 s55, s55, s56
	s_waitcnt vmcnt(19)
	v_mfma_f32_16x16x32_bf16 v[160:163], v[96:99], v[64:67], 0
	s_waitcnt vmcnt(18)
	v_mfma_f32_16x16x32_bf16 v[160:163], v[100:103], v[68:71], v[160:163]
	s_waitcnt vmcnt(17)
	v_mfma_f32_16x16x32_bf16 v[160:163], v[104:107], v[72:75], v[160:163]
	s_waitcnt vmcnt(16)
	v_mfma_f32_16x16x32_bf16 v[160:163], v[108:111], v[76:79], v[160:163]
	s_waitcnt vmcnt(15)
	v_mfma_f32_16x16x32_bf16 v[164:167], v[112:115], v[64:67], 0
	s_waitcnt vmcnt(14)
	v_mfma_f32_16x16x32_bf16 v[164:167], v[116:119], v[68:71], v[164:167]
	s_waitcnt vmcnt(13)
	v_mfma_f32_16x16x32_bf16 v[164:167], v[120:123], v[72:75], v[164:167]
	s_waitcnt vmcnt(12)
	v_mfma_f32_16x16x32_bf16 v[164:167], v[124:127], v[76:79], v[164:167]
	s_waitcnt vmcnt(11)
	v_mfma_f32_16x16x32_bf16 v[168:171], v[128:131], v[64:67], 0
	s_waitcnt vmcnt(10)
	v_mfma_f32_16x16x32_bf16 v[168:171], v[132:135], v[68:71], v[168:171]
	s_waitcnt vmcnt(9)
	v_mfma_f32_16x16x32_bf16 v[168:171], v[136:139], v[72:75], v[168:171]
	s_waitcnt vmcnt(8)
	v_mfma_f32_16x16x32_bf16 v[168:171], v[140:143], v[76:79], v[168:171]
	ds_write_b128 v201, v[160:163]
	s_waitcnt vmcnt(7)
	v_mfma_f32_16x16x32_bf16 v[172:175], v[144:147], v[64:67], 0
	s_waitcnt vmcnt(6)
	v_mfma_f32_16x16x32_bf16 v[172:175], v[148:151], v[68:71], v[172:175]
	s_waitcnt vmcnt(5)
	v_mfma_f32_16x16x32_bf16 v[172:175], v[152:155], v[72:75], v[172:175]
	s_waitcnt vmcnt(4)
	v_mfma_f32_16x16x32_bf16 v[172:175], v[156:159], v[76:79], v[172:175]
	ds_write_b128 v201, v[164:167] offset:8192
	s_waitcnt vmcnt(3)
	v_mfma_f32_16x16x32_bf16 v[176:179], v[96:99], v[80:83], 0
	s_waitcnt vmcnt(2)
	v_mfma_f32_16x16x32_bf16 v[176:179], v[100:103], v[84:87], v[176:179]
	s_waitcnt vmcnt(1)
	v_mfma_f32_16x16x32_bf16 v[176:179], v[104:107], v[88:91], v[176:179]
	s_waitcnt vmcnt(0)
	v_mfma_f32_16x16x32_bf16 v[176:179], v[108:111], v[92:95], v[176:179]
	ds_write_b128 v201, v[168:171] offset:16384
	s_waitcnt vmcnt(3)
	v_mfma_f32_16x16x32_bf16 v[180:183], v[112:115], v[80:83], 0
	s_waitcnt vmcnt(2)
	v_mfma_f32_16x16x32_bf16 v[180:183], v[116:119], v[84:87], v[180:183]
	s_waitcnt vmcnt(1)
	v_mfma_f32_16x16x32_bf16 v[180:183], v[120:123], v[88:91], v[180:183]
	s_waitcnt vmcnt(0)
	v_mfma_f32_16x16x32_bf16 v[180:183], v[124:127], v[92:95], v[180:183]
	ds_write_b128 v201, v[172:175] offset:24576
	s_waitcnt vmcnt(3)
	v_mfma_f32_16x16x32_bf16 v[184:187], v[128:131], v[80:83], 0
	s_waitcnt vmcnt(2)
	v_mfma_f32_16x16x32_bf16 v[184:187], v[132:135], v[84:87], v[184:187]
	s_waitcnt vmcnt(1)
	v_mfma_f32_16x16x32_bf16 v[184:187], v[136:139], v[88:91], v[184:187]
	s_waitcnt vmcnt(0)
	v_mfma_f32_16x16x32_bf16 v[184:187], v[140:143], v[92:95], v[184:187]
	ds_write_b128 v201, v[176:179] offset:32768
	s_waitcnt vmcnt(3)
	v_mfma_f32_16x16x32_bf16 v[188:191], v[144:147], v[80:83], 0
	s_waitcnt vmcnt(2)
	v_mfma_f32_16x16x32_bf16 v[188:191], v[148:151], v[84:87], v[188:191]
	s_waitcnt vmcnt(1)
	v_mfma_f32_16x16x32_bf16 v[188:191], v[152:155], v[88:91], v[188:191]
	s_waitcnt vmcnt(0)
	v_mfma_f32_16x16x32_bf16 v[188:191], v[156:159], v[92:95], v[188:191]
	ds_write_b128 v201, v[180:183] offset:40960
	s_nop 7
	ds_write_b128 v201, v[184:187] offset:49152
	ds_write_b128 v201, v[188:191] offset:57344
	s_waitcnt lgkmcnt(0)
	s_barrier
; __device__ __forceinline__ u32x2 pack4(f32x4 v) { u32x2 r; r.x = cvt_pk(v[0], v[1]); r.y = cvt_pk(v[2], v[3]); return r; }
; __device__ __forceinline__ int lane_fresh() { int l; asm volatile("v_mbcnt_lo_u32_b32 %0, -1, 0\n\tv_mbcnt_hi_u32_b32 %0, -1, %0" : "=v"(l)); return l; }
; __device__ __forceinline__ float shfl_xor_f(float v, int mask) { const int l = lane_fresh(); return __int_as_float(__builtin_amdgcn_ds_bpermute((l ^ mask) << 2, __float_as_int(v))); }
; __device__ __forceinline__ void phaseF(const Params& p, const int wv, const int rep) {
;     ...
;     {
;       const int lane_e = lane_fresh(), fr = lane_e & 15, fq = lane_e >> 4;
;       const int ntl = nt0 + wv, row = TP + mt * 16 + fr, col = ntl * 16 + fq * 4;
;       const float* ps = PSS + (size_t)(row - TP) * 64 + fq * 16;
;       f32x4 a4 = *(const f32x4*)ps + *(const f32x4*)(ps + 4) + *(const f32x4*)(ps + 8) + *(const f32x4*)(ps + 12);
;       float sq = a4[0] + a4[1] + a4[2] + a4[3];
;       sq += shfl_xor_f(sq, 16); sq += shfl_xor_f(sq, 32);
;       const float rstd = rsqrtf(sq * (1.f / 1024.f) + EPS);
;       f32x4 v = skreduce(wv) * rstd;
; #pragma unroll
;       for (int e = 0; e < 4; ++e) { float r = fmaxf(v[e], 0.f); v[e] = r * r; }
;       *(u32x2*)(ACT + (size_t)row * 4096 + col) = pack4(v);
;     }
	s_lshr_b32 s28, s90, 2
	s_lshl_b32 s28, s28, 4
	s_add_i32 s28, s28, s99
	s_and_b32 s45, s90, 3
	s_add_i32 s45, s45, s98
	v_mbcnt_lo_u32_b32 v0, -1, 0
	v_mbcnt_hi_u32_b32 v0, -1, v0
	s_nop 0
	v_and_or_b32 v20, v0, 15, s28
	v_ashrrev_i32_e32 v21, 31, v20
	v_and_b32_e32 v4, -16, v0
	v_lshlrev_b64 v[6:7], 8, v[20:21]
	v_ashrrev_i32_e32 v5, 31, v4
	v_lshl_add_u64 v[6:7], s[10:11], 0, v[6:7]
	v_lshl_add_u64 v[4:5], v[4:5], 2, v[6:7]
	v_lshl_add_u64 v[16:17], v[4:5], 0, s[26:27]
	v_add_co_u32_e32 v4, vcc, s41, v4
	v_ashrrev_i32_e32 v0, 2, v0
	s_nop 0
	v_addc_co_u32_e32 v5, vcc, -1, v5, vcc
	v_mov_b32_e32 v4, v204
	v_mov_b32_e32 v5, v205
	v_mov_b32_e32 v6, v206
	v_mov_b32_e32 v7, v207
	s_nop 0
	v_mov_b32_e32 v8, v208
	v_mov_b32_e32 v9, v209
	v_mov_b32_e32 v10, v210
	v_mov_b32_e32 v11, v211
	v_mov_b32_e32 v12, v212
	v_mov_b32_e32 v13, v213
	v_mov_b32_e32 v14, v214
	v_mov_b32_e32 v15, v215
	s_nop 0
	v_mov_b32_e32 v16, v216
	v_mov_b32_e32 v17, v217
	v_mov_b32_e32 v18, v218
	v_mov_b32_e32 v19, v219
	v_and_b32_e32 v0, -4, v0
	v_lshl_add_u32 v22, s45, 4, v0
	v_mbcnt_lo_u32_b32 v0, -1, 0
	v_mbcnt_hi_u32_b32 v0, -1, v0
	v_mbcnt_lo_u32_b32 v3, -1, 0
	v_mbcnt_hi_u32_b32 v3, -1, v3
	v_lshlrev_b64 v[20:21], 13, v[20:21]
	v_lshlrev_b32_e32 v0, 2, v0
	v_xor_b32_e32 v0, 64, v0
	v_lshlrev_b32_e32 v3, 2, v3
	v_xor_b32_e32 v3, 0x80, v3
	v_lshl_add_u64 v[20:21], s[2:3], 0, v[20:21]
	v_ashrrev_i32_e32 v23, 31, v22
	v_lshl_add_u64 v[52:53], v[22:23], 1, v[20:21]
	v_mbcnt_lo_u32_b32 v20, -1, 0
	v_mbcnt_hi_u32_b32 v20, -1, v20
	s_waitcnt vmcnt(2)
	v_pk_add_f32 v[4:5], v[4:5], v[8:9]
	v_pk_add_f32 v[6:7], v[6:7], v[10:11]
	s_waitcnt vmcnt(1)
	v_pk_add_f32 v[4:5], v[4:5], v[12:13]
	v_pk_add_f32 v[6:7], v[6:7], v[14:15]
	s_waitcnt vmcnt(0)
	v_pk_add_f32 v[4:5], v[4:5], v[16:17]
	v_pk_add_f32 v[6:7], v[6:7], v[18:19]
	v_add_f32_e32 v4, v4, v5
	v_add_f32_e32 v4, v6, v4
	v_add_f32_e32 v4, v7, v4
	ds_bpermute_b32 v0, v0, v4
	v_lshl_add_u32 v48, v20, 4, s31
	ds_read_b128 v[20:23], v48
	ds_read_b128 v[24:27], v48 offset:1024
	ds_read_b128 v[28:31], v48 offset:2048
	ds_read_b128 v[32:35], v48 offset:3072
	ds_read_b128 v[36:39], v48 offset:4096
	ds_read_b128 v[40:43], v48 offset:5120
	ds_read_b128 v[44:47], v48 offset:6144
	ds_read_b128 v[48:51], v48 offset:7168
	s_waitcnt lgkmcnt(7)
	v_pk_add_f32 v[22:23], v[22:23], 0 op_sel_hi:[1,0]
	v_pk_add_f32 v[20:21], v[20:21], 0 op_sel_hi:[1,0]
	v_add_f32_e32 v0, v4, v0
	ds_bpermute_b32 v3, v3, v0
	s_waitcnt lgkmcnt(7)
	v_pk_add_f32 v[22:23], v[22:23], v[26:27]
	v_pk_add_f32 v[20:21], v[20:21], v[24:25]
	s_waitcnt lgkmcnt(6)
	v_pk_add_f32 v[22:23], v[22:23], v[30:31]
	v_pk_add_f32 v[20:21], v[20:21], v[28:29]
	s_waitcnt lgkmcnt(0)
	v_add_f32_e32 v0, v0, v3
	v_fmamk_f32 v0, v0, 0x3a800000, v2
	v_mul_f32_e32 v3, 0x4b800000, v0
	v_cmp_gt_f32_e32 vcc, s42, v0
	v_pk_add_f32 v[22:23], v[22:23], v[34:35]
	v_pk_add_f32 v[20:21], v[20:21], v[32:33]
	v_cndmask_b32_e32 v0, v0, v3, vcc
	v_rsq_f32_e32 v0, v0
	v_pk_add_f32 v[22:23], v[22:23], v[38:39]
	v_pk_add_f32 v[20:21], v[20:21], v[36:37]
	v_pk_add_f32 v[22:23], v[22:23], v[42:43]
	v_pk_add_f32 v[20:21], v[20:21], v[40:41]
	v_pk_add_f32 v[22:23], v[22:23], v[46:47]
	v_pk_add_f32 v[20:21], v[20:21], v[44:45]
	v_mul_f32_e32 v3, 0x45800000, v0
	v_pk_add_f32 v[22:23], v[22:23], v[50:51]
	v_pk_add_f32 v[20:21], v[20:21], v[48:49]
	v_cndmask_b32_e32 v0, v0, v3, vcc
	v_pk_mul_f32 v[4:5], v[22:23], v[0:1] op_sel_hi:[1,0]
	v_pk_mul_f32 v[6:7], v[20:21], v[0:1] op_sel_hi:[1,0]
	v_max_f32_e32 v4, 0, v4
	v_max_f32_e32 v6, 0, v6
	v_max_f32_e32 v7, 0, v7
	v_max_f32_e32 v5, 0, v5
	v_pk_mul_f32 v[6:7], v[6:7], v[6:7]
	v_pk_mul_f32 v[4:5], v[4:5], v[4:5]
	v_cvt_pk_bf16_f32 v6, v6, v7
	v_cvt_pk_bf16_f32 v7, v4, v5
	global_store_dwordx2 v[52:53], v[6:7], off
	s_cmpk_lt_i32 s43, 0x100
	s_cbranch_scc1 .LBB0_1077

; __global__ void __launch_bounds__(NTHREADS) fwd_megakernel(Params p) {
;   cg::grid_group grid = cg::this_grid();
;   const int wv = __builtin_amdgcn_readfirstlane(threadIdx.x >> 6);
	.amdhsa_kernel _Z14fwd_megakernel6Params
		.amdhsa_group_segment_fixed_size 16
		.amdhsa_private_segment_fixed_size 0
		.amdhsa_kernarg_size 512
		.amdhsa_user_sgpr_count 2
		.amdhsa_user_sgpr_dispatch_ptr 0
		.amdhsa_user_sgpr_queue_ptr 0
		.amdhsa_user_sgpr_kernarg_segment_ptr 1
		.amdhsa_user_sgpr_dispatch_id 0
		.amdhsa_user_sgpr_kernarg_preload_length 0
		.amdhsa_user_sgpr_kernarg_preload_offset 0
		.amdhsa_user_sgpr_private_segment_size 0
		.amdhsa_uses_dynamic_stack 0
		.amdhsa_enable_private_segment 0
		.amdhsa_system_sgpr_workgroup_id_x 1
		.amdhsa_system_sgpr_workgroup_id_y 0
		.amdhsa_system_sgpr_workgroup_id_z 0
		.amdhsa_system_sgpr_workgroup_info 0
		.amdhsa_system_vgpr_workitem_id 2
		.amdhsa_next_free_vgpr 252
		.amdhsa_next_free_sgpr 102
		.amdhsa_accum_offset 252
		.amdhsa_reserve_vcc 1
		.amdhsa_float_round_mode_32 0
		.amdhsa_float_round_mode_16_64 0
		.amdhsa_float_denorm_mode_32 3
		.amdhsa_float_denorm_mode_16_64 3
		.amdhsa_dx10_clamp 1
		.amdhsa_ieee_mode 1
		.amdhsa_fp16_overflow 0
		.amdhsa_tg_split 0
		.amdhsa_exception_fp_ieee_invalid_op 0
		.amdhsa_exception_fp_denorm_src 0
		.amdhsa_exception_fp_ieee_div_zero 0
		.amdhsa_exception_fp_ieee_overflow 0
		.amdhsa_exception_fp_ieee_underflow 0
		.amdhsa_exception_fp_ieee_inexact 0
		.amdhsa_exception_int_div_zero 0
	.end_amdhsa_kernel

; __global__ void __launch_bounds__(NTHREADS) fwd_megakernel(Params p) {
amdhsa.kernels:
  - .agpr_count:     0
    .args:
      - .offset:         0
        .size:           256
        .value_kind:     by_value
      - .offset:         256
        .size:           4
        .value_kind:     hidden_block_count_x
      - .offset:         260
        .size:           4
        .value_kind:     hidden_block_count_y
      - .offset:         264
        .size:           4
        .value_kind:     hidden_block_count_z
      - .offset:         268
        .size:           2
        .value_kind:     hidden_group_size_x
      - .offset:         270
        .size:           2
        .value_kind:     hidden_group_size_y
      - .offset:         272
        .size:           2
        .value_kind:     hidden_group_size_z
      - .offset:         274
        .size:           2
        .value_kind:     hidden_remainder_x
      - .offset:         276
        .size:           2
        .value_kind:     hidden_remainder_y
      - .offset:         278
        .size:           2
        .value_kind:     hidden_remainder_z
      - .offset:         296
        .size:           8
        .value_kind:     hidden_global_offset_x
      - .offset:         304
        .size:           8
        .value_kind:     hidden_global_offset_y
      - .offset:         312
        .size:           8
        .value_kind:     hidden_global_offset_z
      - .offset:         320
        .size:           2
        .value_kind:     hidden_grid_dims
      - .offset:         344
        .size:           8
        .value_kind:     hidden_multigrid_sync_arg
      - .offset:         376
        .size:           4
        .value_kind:     hidden_dynamic_lds_size
    .group_segment_fixed_size: 16
    .kernarg_segment_align: 8
    .kernarg_segment_size: 512
    .language:       OpenCL C
    .language_version:
      - 2
      - 0
    .max_flat_workgroup_size: 512
    .name:           _Z14fwd_megakernel6Params
    .private_segment_fixed_size: 0
    .sgpr_count:     108
    .sgpr_spill_count: 126
    .symbol:         _Z14fwd_megakernel6Params.kd
    .uniform_work_group_size: 1
    .uses_dynamic_stack: false
    .vgpr_count:     252
    .vgpr_spill_count: 0
    .wavefront_size: 64
